# fp8 gate GEMM: 4x v_mfma_16x16x32_fp8_fp8 replaced by one v_mfma_16x16x128_f8f6f4 (same fp8 operands, f32 acc); plus lru ugv hoist + conv weights via LDS
# speedup vs baseline: 1.0108x; 1.0108x over previous
.LBB0_344:
	ds_read_b128 v[152:155], v182
	ds_read_b128 v[156:159], v182 offset:1024
	ds_read_b128 v[144:147], v182 offset:2048
	ds_read_b128 v[148:151], v182 offset:3072
	ds_read_b128 v[136:139], v183
	ds_read_b128 v[140:143], v183 offset:1024
	ds_read_b128 v[128:131], v183 offset:2048
	ds_read_b128 v[132:135], v183 offset:3072
	s_add_u32 s54, s52, 0xfffe0080
	s_addc_u32 s55, s53, -1
	s_cmp_eq_u32 s58, 4
	s_cselect_b32 s57, s49, s55
	s_cselect_b32 s56, s48, s54
	s_cselect_b32 s55, s51, s47
	s_cselect_b32 s54, s50, s39
	v_lshl_add_u64 v[210:211], s[52:53], 0, v[168:169]
	s_add_i32 m0, s25, 0xc000
	ds_read_b128 v[172:175], v184
	ds_read_b128 v[176:179], v184 offset:1024
	ds_read_b128 v[186:189], v184 offset:2048
	ds_read_b128 v[190:193], v184 offset:3072
	ds_read_b128 v[194:197], v184 offset:4096
	ds_read_b128 v[198:201], v184 offset:5120
	ds_read_b128 v[202:205], v184 offset:6144
	ds_read_b128 v[206:209], v184 offset:7168
	global_load_lds_dwordx4 v[210:211], off
	v_lshl_add_u64 v[210:211], s[52:53], 0, v[170:171]
	s_add_i32 m0, s25, 0xe000
	s_nop 0
	global_load_lds_dwordx4 v[210:211], off
	s_waitcnt vmcnt(8)
	s_waitcnt lgkmcnt(0)
	s_barrier
	s_setprio 1
	s_waitcnt lgkmcnt(0)
	v_mfma_f32_16x16x128_f8f6f4 v[124:127], v[152:159], v[172:179], v[124:127]
	v_mfma_f32_16x16x128_f8f6f4 v[120:123], v[144:151], v[172:179], v[120:123]
	v_mfma_f32_16x16x128_f8f6f4 v[108:111], v[152:159], v[186:193], v[108:111]
	v_mfma_f32_16x16x128_f8f6f4 v[104:107], v[144:151], v[186:193], v[104:107]
	v_mfma_f32_16x16x128_f8f6f4 v[92:95], v[152:159], v[194:201], v[92:95]
	v_mfma_f32_16x16x128_f8f6f4 v[88:91], v[144:151], v[194:201], v[88:91]
	v_mfma_f32_16x16x128_f8f6f4 v[76:79], v[152:159], v[202:209], v[76:79]
	v_mfma_f32_16x16x128_f8f6f4 v[72:75], v[144:151], v[202:209], v[72:75]
	s_setprio 0
	s_setprio 1
	v_mfma_f32_16x16x128_f8f6f4 v[116:119], v[136:143], v[172:179], v[116:119]
	v_mfma_f32_16x16x128_f8f6f4 v[112:115], v[128:135], v[172:179], v[112:115]
	v_mfma_f32_16x16x128_f8f6f4 v[100:103], v[136:143], v[186:193], v[100:103]
	v_mfma_f32_16x16x128_f8f6f4 v[96:99], v[128:135], v[186:193], v[96:99]
	v_mfma_f32_16x16x128_f8f6f4 v[84:87], v[136:143], v[194:201], v[84:87]
	v_mfma_f32_16x16x128_f8f6f4 v[80:83], v[128:135], v[194:201], v[80:83]
	v_mfma_f32_16x16x128_f8f6f4 v[68:71], v[136:143], v[202:209], v[68:71]
	v_mfma_f32_16x16x128_f8f6f4 v[64:67], v[128:135], v[202:209], v[64:67]
	s_setprio 0
	s_barrier
	s_add_i32 s59, s35, s24
	v_lshl_add_u64 v[172:173], s[54:55], 0, v[164:165]
	s_mov_b32 m0, s59
	ds_read_b128 v[186:189], v184 offset:16384
	ds_read_b128 v[190:193], v184 offset:17408
	ds_read_b128 v[194:197], v184 offset:18432
	ds_read_b128 v[198:201], v184 offset:19456
	ds_read_b128 v[202:205], v184 offset:20480
	ds_read_b128 v[206:209], v184 offset:21504
	ds_read_b128 v[210:213], v184 offset:22528
	ds_read_b128 v[214:217], v184 offset:23552
	global_load_lds_dwordx4 v[172:173], off
	s_add_i32 m0, s59, 0x2000
	s_add_u32 s60, s54, 0x20000
	v_lshl_add_u64 v[174:175], s[54:55], 0, v[160:161]
	s_addc_u32 s61, s55, 0
	s_add_i32 s59, s37, s24
	global_load_lds_dwordx4 v[174:175], off
	v_lshl_add_u64 v[176:177], s[60:61], 0, v[164:165]
	s_mov_b32 m0, s59
	v_lshl_add_u64 v[178:179], s[56:57], 0, v[162:163]
	global_load_lds_dwordx4 v[176:177], off
	v_lshl_add_u64 v[176:177], s[60:61], 0, v[160:161]
	s_add_i32 m0, s59, 0x2000
	s_nop 0
	global_load_lds_dwordx4 v[176:177], off
	v_lshl_add_u64 v[176:177], s[56:57], 0, v[166:167]
	s_mov_b32 m0, s25
	s_nop 0
	global_load_lds_dwordx4 v[176:177], off
	s_mov_b32 m0, s26
	s_nop 0
	global_load_lds_dwordx4 v[178:179], off
	s_waitcnt vmcnt(8)
	s_waitcnt lgkmcnt(0)
	s_barrier
	s_setprio 1
	s_waitcnt lgkmcnt(0)
	v_mfma_f32_16x16x128_f8f6f4 v[60:63], v[152:159], v[186:193], v[60:63]
	v_mfma_f32_16x16x128_f8f6f4 v[56:59], v[144:151], v[186:193], v[56:59]
	v_mfma_f32_16x16x128_f8f6f4 v[44:47], v[152:159], v[194:201], v[44:47]
	v_mfma_f32_16x16x128_f8f6f4 v[40:43], v[144:151], v[194:201], v[40:43]
	v_mfma_f32_16x16x128_f8f6f4 v[28:31], v[152:159], v[202:209], v[28:31]
	v_mfma_f32_16x16x128_f8f6f4 v[24:27], v[144:151], v[202:209], v[24:27]
	v_mfma_f32_16x16x128_f8f6f4 v[12:15], v[152:159], v[210:217], v[12:15]
	v_mfma_f32_16x16x128_f8f6f4 v[8:11], v[144:151], v[210:217], v[8:11]
	s_setprio 0
	s_setprio 1
	v_mfma_f32_16x16x128_f8f6f4 v[52:55], v[136:143], v[186:193], v[52:55]
	v_mfma_f32_16x16x128_f8f6f4 v[48:51], v[128:135], v[186:193], v[48:51]
	v_mfma_f32_16x16x128_f8f6f4 v[36:39], v[136:143], v[194:201], v[36:39]
	v_mfma_f32_16x16x128_f8f6f4 v[32:35], v[128:135], v[194:201], v[32:35]
	v_mfma_f32_16x16x128_f8f6f4 v[20:23], v[136:143], v[202:209], v[20:23]
	v_mfma_f32_16x16x128_f8f6f4 v[16:19], v[128:135], v[202:209], v[16:19]
	v_mfma_f32_16x16x128_f8f6f4 v[4:7], v[136:143], v[210:217], v[4:7]
	v_mfma_f32_16x16x128_f8f6f4 v[0:3], v[128:135], v[210:217], v[0:3]
	s_setprio 0
	s_barrier
	s_add_i32 s59, 0, 0x18000
	v_add_u32_e32 v128, s59, v181
	s_add_i32 s60, 0, 0x1c000
	ds_read_b128 v[152:155], v128
	ds_read_b128 v[156:159], v128 offset:1024
	ds_read_b128 v[144:147], v128 offset:2048
	ds_read_b128 v[148:151], v128 offset:3072
	v_add_u32_e32 v128, s60, v181
	ds_read_b128 v[136:139], v128
	ds_read_b128 v[140:143], v128 offset:1024
	ds_read_b128 v[132:135], v128 offset:3072
	ds_read_b128 v[128:131], v128 offset:2048
	s_add_u32 s56, s56, 0x20000
	s_addc_u32 s57, s57, 0
	s_mov_b32 m0, s27
	v_lshl_add_u64 v[218:219], s[56:57], 0, v[166:167]
	ds_read_b128 v[186:189], v184 offset:32768
	ds_read_b128 v[190:193], v184 offset:33792
	ds_read_b128 v[194:197], v184 offset:34816
	ds_read_b128 v[198:201], v184 offset:35840
	ds_read_b128 v[202:205], v184 offset:36864
	ds_read_b128 v[206:209], v184 offset:37888
	ds_read_b128 v[210:213], v184 offset:38912
	ds_read_b128 v[214:217], v184 offset:39936
	global_load_lds_dwordx4 v[218:219], off
	v_lshl_add_u64 v[218:219], s[56:57], 0, v[162:163]
	s_mov_b32 m0, s28
	s_nop 0
	global_load_lds_dwordx4 v[218:219], off
	s_waitcnt vmcnt(8)
	s_waitcnt lgkmcnt(0)
	s_barrier
	s_setprio 1
	s_waitcnt lgkmcnt(0)
	v_mfma_f32_16x16x128_f8f6f4 v[124:127], v[152:159], v[186:193], v[124:127]
	v_mfma_f32_16x16x128_f8f6f4 v[120:123], v[144:151], v[186:193], v[120:123]
	v_mfma_f32_16x16x128_f8f6f4 v[108:111], v[152:159], v[194:201], v[108:111]
	v_mfma_f32_16x16x128_f8f6f4 v[104:107], v[144:151], v[194:201], v[104:107]
	v_mfma_f32_16x16x128_f8f6f4 v[92:95], v[152:159], v[202:209], v[92:95]
	v_mfma_f32_16x16x128_f8f6f4 v[88:91], v[144:151], v[202:209], v[88:91]
	v_mfma_f32_16x16x128_f8f6f4 v[76:79], v[152:159], v[210:217], v[76:79]
	v_mfma_f32_16x16x128_f8f6f4 v[72:75], v[144:151], v[210:217], v[72:75]
	s_setprio 0
	s_setprio 1
	v_mfma_f32_16x16x128_f8f6f4 v[116:119], v[136:143], v[186:193], v[116:119]
	v_mfma_f32_16x16x128_f8f6f4 v[112:115], v[128:135], v[186:193], v[112:115]
	v_mfma_f32_16x16x128_f8f6f4 v[100:103], v[136:143], v[194:201], v[100:103]
	v_mfma_f32_16x16x128_f8f6f4 v[96:99], v[128:135], v[194:201], v[96:99]
	v_mfma_f32_16x16x128_f8f6f4 v[84:87], v[136:143], v[202:209], v[84:87]
	v_mfma_f32_16x16x128_f8f6f4 v[80:83], v[128:135], v[202:209], v[80:83]
	v_mfma_f32_16x16x128_f8f6f4 v[68:71], v[136:143], v[210:217], v[68:71]
	v_mfma_f32_16x16x128_f8f6f4 v[64:67], v[128:135], v[210:217], v[64:67]
	s_setprio 0
	s_barrier
	s_add_i32 s56, s59, s24
	v_lshl_add_u64 v[172:173], v[172:173], 0, s[6:7]
	s_mov_b32 m0, s56
	ds_read_b128 v[186:189], v184 offset:49152
	ds_read_b128 v[190:193], v184 offset:50176
	ds_read_b128 v[194:197], v184 offset:51200
	ds_read_b128 v[198:201], v184 offset:52224
	ds_read_b128 v[202:205], v184 offset:53248
	ds_read_b128 v[206:209], v184 offset:54272
	ds_read_b128 v[210:213], v184 offset:55296
	ds_read_b128 v[214:217], v184 offset:56320
	global_load_lds_dwordx4 v[172:173], off
	s_add_i32 m0, s56, 0x2000
	s_add_u32 s54, s54, 0x20080
	v_lshl_add_u64 v[172:173], v[174:175], 0, s[6:7]
	s_addc_u32 s55, s55, 0
	s_add_i32 s56, s60, s24
	global_load_lds_dwordx4 v[172:173], off
	v_lshl_add_u64 v[172:173], s[54:55], 0, v[164:165]
	s_mov_b32 m0, s56
	s_nop 0
	global_load_lds_dwordx4 v[172:173], off
	v_lshl_add_u64 v[172:173], s[54:55], 0, v[160:161]
	s_add_i32 m0, s56, 0x2000
	s_nop 0
	global_load_lds_dwordx4 v[172:173], off
	v_lshl_add_u64 v[172:173], v[176:177], 0, s[6:7]
	s_mov_b32 m0, s33
	s_nop 0
	global_load_lds_dwordx4 v[172:173], off
	v_lshl_add_u64 v[172:173], v[178:179], 0, s[6:7]
	s_mov_b32 m0, s34
	s_nop 0
	global_load_lds_dwordx4 v[172:173], off
	s_waitcnt vmcnt(8)
	s_waitcnt lgkmcnt(0)
	s_barrier
	s_setprio 1
	s_waitcnt lgkmcnt(0)
	v_mfma_f32_16x16x128_f8f6f4 v[60:63], v[152:159], v[186:193], v[60:63]
	v_mfma_f32_16x16x128_f8f6f4 v[56:59], v[144:151], v[186:193], v[56:59]
	v_mfma_f32_16x16x128_f8f6f4 v[44:47], v[152:159], v[194:201], v[44:47]
	v_mfma_f32_16x16x128_f8f6f4 v[40:43], v[144:151], v[194:201], v[40:43]
	v_mfma_f32_16x16x128_f8f6f4 v[28:31], v[152:159], v[202:209], v[28:31]
	v_mfma_f32_16x16x128_f8f6f4 v[24:27], v[144:151], v[202:209], v[24:27]
	v_mfma_f32_16x16x128_f8f6f4 v[12:15], v[152:159], v[210:217], v[12:15]
	v_mfma_f32_16x16x128_f8f6f4 v[8:11], v[144:151], v[210:217], v[8:11]
	s_setprio 0
	s_setprio 1
	v_mfma_f32_16x16x128_f8f6f4 v[52:55], v[136:143], v[186:193], v[52:55]
	v_mfma_f32_16x16x128_f8f6f4 v[48:51], v[128:135], v[186:193], v[48:51]
	v_mfma_f32_16x16x128_f8f6f4 v[36:39], v[136:143], v[194:201], v[36:39]
	v_mfma_f32_16x16x128_f8f6f4 v[32:35], v[128:135], v[194:201], v[32:35]
	v_mfma_f32_16x16x128_f8f6f4 v[20:23], v[136:143], v[202:209], v[20:23]
	v_mfma_f32_16x16x128_f8f6f4 v[16:19], v[128:135], v[202:209], v[16:19]
	v_mfma_f32_16x16x128_f8f6f4 v[4:7], v[136:143], v[210:217], v[4:7]
	v_mfma_f32_16x16x128_f8f6f4 v[0:3], v[128:135], v[210:217], v[0:3]
	s_setprio 0
	s_barrier
	s_add_i32 s58, s58, 2
	s_add_u32 s52, s52, 0x100
	s_addc_u32 s53, s53, 0
	s_add_u32 s39, s39, 0x100
	s_addc_u32 s47, s47, 0
	s_cmp_gt_u32 s58, 5
	s_cbranch_scc0 .LBB0_344
	s_and_b64 vcc, exec, s[8:9]
	v_readlane_b32 s58, v247, 26
	v_readlane_b32 s59, v247, 27
	s_cbranch_vccz .LBB0_347
	s_barrier
